# C + all eight GEMM K-loop heads padded to byte phase 48 mod 64 (code placement)
# baseline (speedup 1.0000x reference)
;     __device__ bool next(int i, Unit& u) const { if (i != 0) return false; return so.next(round, u); }
;     __device__ __forceinline__ bool next(int i, Unit& u) const { if (i > 0 || !on) return false; u.pm = pm; u.pn = 0; return true; }
; #define PG8_STAGE(bufoff, gbase, voff) do { _Pragma("unroll") for (int _i = 0; _i < 2; ++_i) \
;         __builtin_amdgcn_global_load_lds((const unsigned*)((const char*)(gbase) + (voff)[_i]), (PG8_LAS unsigned*)(lds + (bufoff) + ldsw + _i * 8192), 16, 0, 0); } while (0)
; #define PG8_LDA(dst, b, h) do { _Pragma("unroll") for (int m = 0; m < 4; ++m) _Pragma("unroll") for (int k = 0; k < 2; ++k) dst[m][k] = *(const PG8_LAS bf16x8*)(lds + PG8_SA(b, h) + aoff + m * 2048 + k * 1024); } while (0)
; #define PG8_LDB(dst, b, h) do { _Pragma("unroll") for (int n = 0; n < 2; ++n) _Pragma("unroll") for (int k = 0; k < 2; ++k) dst[n][k] = *(const PG8_LAS bf16x8*)(lds + PG8_SB(b, h) + boff + n * 2048 + k * 1024); } while (0)
; #define PG8_WAIT_V(n) asm volatile("s_waitcnt vmcnt(" #n ")" ::: "memory")
; #define PG8_WAIT_L(n) asm volatile("s_waitcnt lgkmcnt(" #n ")" ::: "memory")
; #define PG8_BAR __builtin_amdgcn_s_barrier()
; template <class Epi, class Sched, bool ALIGN_EPI = false, bool SP2 = false, bool MIDHOOK = false>
; __device__ __forceinline__ void gemm_phase(PG8_LAS unsigned char* lds, const Gemm g, const Sched& S, const Epi& E) {
;     ...
;         const bool has_next = S.next(ui + 1, nxt);
;         const char* nA = has_next ? (const char*)g.A + (size_t)nxt.pm * tstep : cA; const char* nB = has_next ? (const char*)g.Bt + (size_t)nxt.pn * tstep : cB;
;         for (int t = 0; t < nt; t += 2) {
;             if constexpr (MIDHOOK) { if (t == nt / 2) E.mid(acc, cur, wr, wc, fr, fq); }
;             const bool last = (t == nt - 2);
;             const char* a1 = cA + (size_t)(t + 1) * kstep;
;             const char* a2 = last ? nA : cA + (size_t)(t + 2) * kstep; const char* b2 = last ? nB : cB + (size_t)(t + 2) * kstep;
;             const char* a3 = a2 + kstep; const char* b3 = b2 + kstep;
;             if (last && has_next) S.a_ready(nxt);
;             if constexpr (SP2) {
;             PG8_LDB(B0, 0, 0); PG8_LDB(B1, 0, 1); PG8_SCHED; PG8_LDA(At, 0, 0); PG8_STAGE(PG8_SA(1, 1), a1 + hstep, voffA);
;             PG8_WAIT_V(8); PG8_WAIT_L(0); PG8_BAR; PG8_MMA(0, 0, At, B0); PG8_MMA(0, 1, At, B1); PG8_BAR; PG8_SCHED;
.LBB0_190:
	s_ashr_i32 s41, s40, 31
	s_lshl_b64 s[42:43], s[40:41], 19
	v_readlane_b32 s12, v243, 48
	v_readlane_b32 s13, v243, 49
	s_add_u32 s42, s12, s42
	s_addc_u32 s43, s13, s43
	s_and_b64 s[44:45], s[0:1], exec
	s_cselect_b32 s5, s43, s7
	s_cselect_b32 s41, s42, s6
	s_ashr_i32 s39, s38, 31
	s_lshl_b64 s[44:45], s[38:39], 19
	s_add_u32 s44, s24, s44
	s_addc_u32 s45, s25, s45
	s_and_b64 s[48:49], s[0:1], exec
	s_cselect_b32 s39, s45, s9
	s_cselect_b32 s62, s44, s8
	s_add_u32 s6, s6, 0x40080
	s_addc_u32 s7, s7, 0
	s_add_u32 s63, s8, 0x100
	v_mov_b32_e32 v0, 0
	s_addc_u32 s64, s9, 0
	s_mov_b32 s65, -2
	v_mov_b32_e32 v1, v0
	v_mov_b32_e32 v2, v0
	v_mov_b32_e32 v3, v0
	v_mov_b32_e32 v8, v0
	v_mov_b32_e32 v9, v0
	v_mov_b32_e32 v10, v0
	v_mov_b32_e32 v11, v0
	v_mov_b32_e32 v16, v0
	v_mov_b32_e32 v17, v0
	v_mov_b32_e32 v18, v0
	v_mov_b32_e32 v19, v0
	v_mov_b32_e32 v24, v0
	v_mov_b32_e32 v25, v0
	v_mov_b32_e32 v26, v0
	v_mov_b32_e32 v27, v0
	v_mov_b32_e32 v32, v0
	v_mov_b32_e32 v33, v0
	v_mov_b32_e32 v34, v0
	v_mov_b32_e32 v35, v0
	v_mov_b32_e32 v40, v0
	v_mov_b32_e32 v41, v0
	v_mov_b32_e32 v42, v0
	v_mov_b32_e32 v43, v0
	v_mov_b32_e32 v48, v0
	v_mov_b32_e32 v49, v0
	v_mov_b32_e32 v50, v0
	v_mov_b32_e32 v51, v0
	v_mov_b32_e32 v56, v0
	v_mov_b32_e32 v57, v0
	v_mov_b32_e32 v58, v0
	v_mov_b32_e32 v59, v0
	v_mov_b32_e32 v4, v0
	v_mov_b32_e32 v5, v0
	v_mov_b32_e32 v6, v0
	v_mov_b32_e32 v7, v0
	v_mov_b32_e32 v12, v0
	v_mov_b32_e32 v13, v0
	v_mov_b32_e32 v14, v0
	v_mov_b32_e32 v15, v0
	v_mov_b32_e32 v20, v0
	v_mov_b32_e32 v21, v0
	v_mov_b32_e32 v22, v0
	v_mov_b32_e32 v23, v0
	v_mov_b32_e32 v28, v0
	v_mov_b32_e32 v29, v0
	v_mov_b32_e32 v30, v0
	v_mov_b32_e32 v31, v0
	v_mov_b32_e32 v36, v0
	v_mov_b32_e32 v37, v0
	v_mov_b32_e32 v38, v0
	v_mov_b32_e32 v39, v0
	v_mov_b32_e32 v44, v0
	v_mov_b32_e32 v45, v0
	v_mov_b32_e32 v46, v0
	v_mov_b32_e32 v47, v0
	v_mov_b32_e32 v52, v0
	v_mov_b32_e32 v53, v0
	v_mov_b32_e32 v54, v0
	v_mov_b32_e32 v55, v0
	v_mov_b32_e32 v60, v0
	v_mov_b32_e32 v61, v0
	v_mov_b32_e32 v62, v0
	v_mov_b32_e32 v63, v0
	v_mov_b32_e32 v64, v0
	v_mov_b32_e32 v65, v0
	v_mov_b32_e32 v66, v0
	v_mov_b32_e32 v67, v0
	v_mov_b32_e32 v72, v0
	v_mov_b32_e32 v73, v0
	v_mov_b32_e32 v74, v0
	v_mov_b32_e32 v75, v0
	v_mov_b32_e32 v80, v0
	v_mov_b32_e32 v81, v0
	v_mov_b32_e32 v82, v0
	v_mov_b32_e32 v83, v0
	v_mov_b32_e32 v88, v0
	v_mov_b32_e32 v89, v0
	v_mov_b32_e32 v90, v0
	v_mov_b32_e32 v91, v0
	v_mov_b32_e32 v96, v0
	v_mov_b32_e32 v97, v0
	v_mov_b32_e32 v98, v0
	v_mov_b32_e32 v99, v0
	v_mov_b32_e32 v104, v0
	v_mov_b32_e32 v105, v0
	v_mov_b32_e32 v106, v0
	v_mov_b32_e32 v107, v0
	v_mov_b32_e32 v112, v0
	v_mov_b32_e32 v113, v0
	v_mov_b32_e32 v114, v0
	v_mov_b32_e32 v115, v0
	v_mov_b32_e32 v120, v0
	v_mov_b32_e32 v121, v0
	v_mov_b32_e32 v122, v0
	v_mov_b32_e32 v123, v0
	v_mov_b32_e32 v68, v0
	v_mov_b32_e32 v69, v0
	v_mov_b32_e32 v70, v0
	v_mov_b32_e32 v71, v0
	v_mov_b32_e32 v76, v0
	v_mov_b32_e32 v77, v0
	v_mov_b32_e32 v78, v0
	v_mov_b32_e32 v79, v0
	v_mov_b32_e32 v84, v0
	v_mov_b32_e32 v85, v0
	v_mov_b32_e32 v86, v0
	v_mov_b32_e32 v87, v0
	v_mov_b32_e32 v92, v0
	v_mov_b32_e32 v93, v0
	v_mov_b32_e32 v94, v0
	v_mov_b32_e32 v95, v0
	v_mov_b32_e32 v100, v0
	v_mov_b32_e32 v101, v0
	v_mov_b32_e32 v102, v0
	v_mov_b32_e32 v103, v0
	v_mov_b32_e32 v108, v0
	v_mov_b32_e32 v109, v0
	v_mov_b32_e32 v110, v0
	v_mov_b32_e32 v111, v0
	v_mov_b32_e32 v116, v0
	v_mov_b32_e32 v117, v0
	v_mov_b32_e32 v118, v0
	v_mov_b32_e32 v119, v0
	v_mov_b32_e32 v124, v0
	v_mov_b32_e32 v125, v0
	v_mov_b32_e32 v126, v0
	v_mov_b32_e32 v127, v0
	s_nop 0
	s_nop 0
.LBB0_191:
	ds_read_b128 v[128:131], v180
	s_waitcnt vmcnt(0)
	ds_read_b128 v[132:135], v180 offset:1024
	ds_read_b128 v[136:139], v180 offset:2048
	ds_read_b128 v[168:171], v180 offset:3072
	ds_read_b128 v[172:175], v181
	ds_read_b128 v[184:187], v181 offset:1024
	ds_read_b128 v[188:191], v181 offset:2048
	ds_read_b128 v[192:195], v181 offset:3072
	s_add_u32 s8, s6, 0xfffc0080
	s_addc_u32 s9, s7, -1
	s_cmp_eq_u32 s65, 12
	s_cselect_b32 s49, s5, s9
	s_cselect_b32 s48, s41, s8
	s_cselect_b32 s9, s39, s64
	s_cselect_b32 s8, s62, s63
	v_lshl_add_u64 v[230:231], s[6:7], 0, v[156:157]
	s_add_i32 m0, s47, 0xc000
	ds_read_b128 v[196:199], v182
	ds_read_b128 v[200:203], v182 offset:1024
	ds_read_b128 v[204:207], v182 offset:2048
	ds_read_b128 v[208:211], v182 offset:3072
	ds_read_b128 v[212:215], v182 offset:4096
	ds_read_b128 v[216:219], v182 offset:5120
	ds_read_b128 v[222:225], v182 offset:6144
	ds_read_b128 v[226:229], v182 offset:7168
	global_load_lds_dwordx4 v[230:231], off
	v_lshl_add_u64 v[230:231], s[6:7], 0, v[158:159]
	s_add_i32 m0, s47, 0xe000
	s_nop 0
	global_load_lds_dwordx4 v[230:231], off
	s_waitcnt vmcnt(8)
	s_waitcnt lgkmcnt(0)
	s_barrier
; #define PG8_STAGE(bufoff, gbase, voff) do { _Pragma("unroll") for (int _i = 0; _i < 2; ++_i) \
;         __builtin_amdgcn_global_load_lds((const unsigned*)((const char*)(gbase) + (voff)[_i]), (PG8_LAS unsigned*)(lds + (bufoff) + ldsw + _i * 8192), 16, 0, 0); } while (0)
; #define PG8_LDA(dst, b, h) do { _Pragma("unroll") for (int m = 0; m < 4; ++m) _Pragma("unroll") for (int k = 0; k < 2; ++k) dst[m][k] = *(const PG8_LAS bf16x8*)(lds + PG8_SA(b, h) + aoff + m * 2048 + k * 1024); } while (0)
; #define PG8_MMA(ai, bj, At, Bt) do { __builtin_amdgcn_s_setprio(1); _Pragma("unroll") for (int m = 0; m < 4; ++m) _Pragma("unroll") for (int n = 0; n < 2; ++n) _Pragma("unroll") for (int k = 0; k < 2; ++k) \
;         acc[ai][bj][m][n] = __builtin_amdgcn_mfma_f32_16x16x32_bf16(Bt[n][k], At[m][k], acc[ai][bj][m][n], 0, 0, 0); __builtin_amdgcn_s_setprio(0); } while (0)
; #define PG8_WAIT_V(n) asm volatile("s_waitcnt vmcnt(" #n ")" ::: "memory")
; #define PG8_WAIT_L(n) asm volatile("s_waitcnt lgkmcnt(" #n ")" ::: "memory")
; #define PG8_BAR __builtin_amdgcn_s_barrier()
; #define PG8_SCHED __builtin_amdgcn_sched_barrier(0)
; template <class Epi, class Sched, bool ALIGN_EPI = false, bool SP2 = false, bool MIDHOOK = false>
; __device__ __forceinline__ void gemm_phase(PG8_LAS unsigned char* lds, const Gemm g, const Sched& S, const Epi& E) {
;     ...
;             PG8_WAIT_V(8); PG8_WAIT_L(0); PG8_BAR; PG8_MMA(0, 0, At, B0); PG8_MMA(0, 1, At, B1); PG8_BAR; PG8_SCHED;
;             PG8_LDA(At, 0, 1); PG8_STAGE(PG8_SB(0, 0), b2, voffB); PG8_STAGE(PG8_SB(0, 1), b2 + hstep, voffB); PG8_STAGE(PG8_SA(0, 0), a2, voffA);
;             PG8_WAIT_V(8); PG8_WAIT_L(0); PG8_BAR; PG8_MMA(1, 0, At, B0); PG8_MMA(1, 1, At, B1); PG8_BAR; PG8_SCHED;
	s_setprio 1
	s_waitcnt lgkmcnt(0)
	v_mfma_f32_16x16x32_bf16 v[124:127], v[128:131], v[196:199], v[124:127]
	v_mfma_f32_16x16x32_bf16 v[116:119], v[136:139], v[196:199], v[116:119]
	v_mfma_f32_16x16x32_bf16 v[108:111], v[128:131], v[204:207], v[108:111]
	v_mfma_f32_16x16x32_bf16 v[100:103], v[136:139], v[204:207], v[100:103]
	v_mfma_f32_16x16x32_bf16 v[92:95], v[128:131], v[212:215], v[92:95]
	v_mfma_f32_16x16x32_bf16 v[84:87], v[136:139], v[212:215], v[84:87]
	v_mfma_f32_16x16x32_bf16 v[76:79], v[128:131], v[222:225], v[76:79]
	v_mfma_f32_16x16x32_bf16 v[68:71], v[136:139], v[222:225], v[68:71]
	v_mfma_f32_16x16x32_bf16 v[124:127], v[132:135], v[200:203], v[124:127]
	v_mfma_f32_16x16x32_bf16 v[116:119], v[168:171], v[200:203], v[116:119]
	v_mfma_f32_16x16x32_bf16 v[108:111], v[132:135], v[208:211], v[108:111]
	v_mfma_f32_16x16x32_bf16 v[100:103], v[168:171], v[208:211], v[100:103]
	v_mfma_f32_16x16x32_bf16 v[92:95], v[132:135], v[216:219], v[92:95]
	v_mfma_f32_16x16x32_bf16 v[84:87], v[168:171], v[216:219], v[84:87]
	v_mfma_f32_16x16x32_bf16 v[76:79], v[132:135], v[226:229], v[76:79]
	v_mfma_f32_16x16x32_bf16 v[68:71], v[168:171], v[226:229], v[68:71]
	s_setprio 0
	s_setprio 1
	v_mfma_f32_16x16x32_bf16 v[120:123], v[172:175], v[196:199], v[120:123]
	v_mfma_f32_16x16x32_bf16 v[112:115], v[188:191], v[196:199], v[112:115]
	v_mfma_f32_16x16x32_bf16 v[104:107], v[172:175], v[204:207], v[104:107]
	v_mfma_f32_16x16x32_bf16 v[96:99], v[188:191], v[204:207], v[96:99]
	v_mfma_f32_16x16x32_bf16 v[88:91], v[172:175], v[212:215], v[88:91]
	v_mfma_f32_16x16x32_bf16 v[80:83], v[188:191], v[212:215], v[80:83]
	v_mfma_f32_16x16x32_bf16 v[72:75], v[172:175], v[222:225], v[72:75]
	v_mfma_f32_16x16x32_bf16 v[64:67], v[188:191], v[222:225], v[64:67]
	v_mfma_f32_16x16x32_bf16 v[120:123], v[184:187], v[200:203], v[120:123]
	v_mfma_f32_16x16x32_bf16 v[112:115], v[192:195], v[200:203], v[112:115]
	v_mfma_f32_16x16x32_bf16 v[104:107], v[184:187], v[208:211], v[104:107]
	v_mfma_f32_16x16x32_bf16 v[96:99], v[192:195], v[208:211], v[96:99]
	v_mfma_f32_16x16x32_bf16 v[88:91], v[184:187], v[216:219], v[88:91]
	v_mfma_f32_16x16x32_bf16 v[80:83], v[192:195], v[216:219], v[80:83]
	v_mfma_f32_16x16x32_bf16 v[72:75], v[184:187], v[226:229], v[72:75]
	v_mfma_f32_16x16x32_bf16 v[64:67], v[192:195], v[226:229], v[64:67]
	s_setprio 0
	s_barrier
	s_add_i32 s66, s58, s3
	v_lshl_add_u64 v[230:231], s[8:9], 0, v[142:143]
	s_mov_b32 m0, s66
	ds_read_b128 v[196:199], v182 offset:16384
	ds_read_b128 v[200:203], v182 offset:17408
	ds_read_b128 v[204:207], v182 offset:18432
	ds_read_b128 v[208:211], v182 offset:19456
	ds_read_b128 v[212:215], v182 offset:20480
	ds_read_b128 v[216:219], v182 offset:21504
	ds_read_b128 v[222:225], v182 offset:22528
	ds_read_b128 v[226:229], v182 offset:23552
	global_load_lds_dwordx4 v[230:231], off
	s_add_i32 m0, s66, 0x2000
	s_add_u32 s66, s8, 0x40000
	v_lshl_add_u64 v[232:233], s[8:9], 0, v[146:147]
	s_addc_u32 s67, s9, 0
	s_add_i32 s68, s59, s3
	global_load_lds_dwordx4 v[232:233], off
	v_lshl_add_u64 v[234:235], s[66:67], 0, v[142:143]
	s_mov_b32 m0, s68
	v_lshl_add_u64 v[236:237], s[48:49], 0, v[144:145]
	global_load_lds_dwordx4 v[234:235], off
	v_lshl_add_u64 v[234:235], s[66:67], 0, v[146:147]
	s_add_i32 m0, s68, 0x2000
	s_nop 0
	global_load_lds_dwordx4 v[234:235], off
	v_lshl_add_u64 v[234:235], s[48:49], 0, v[140:141]
	s_mov_b32 m0, s47
	s_nop 0
	global_load_lds_dwordx4 v[234:235], off
	s_mov_b32 m0, s50
	s_nop 0
	global_load_lds_dwordx4 v[236:237], off
	s_waitcnt vmcnt(8)
	s_waitcnt lgkmcnt(0)
	s_barrier
	s_setprio 1
	s_waitcnt lgkmcnt(0)
	v_mfma_f32_16x16x32_bf16 v[60:63], v[128:131], v[196:199], v[60:63]
	v_mfma_f32_16x16x32_bf16 v[52:55], v[136:139], v[196:199], v[52:55]
	v_mfma_f32_16x16x32_bf16 v[44:47], v[128:131], v[204:207], v[44:47]
	v_mfma_f32_16x16x32_bf16 v[36:39], v[136:139], v[204:207], v[36:39]
	v_mfma_f32_16x16x32_bf16 v[28:31], v[128:131], v[212:215], v[28:31]
	v_mfma_f32_16x16x32_bf16 v[20:23], v[136:139], v[212:215], v[20:23]
	v_mfma_f32_16x16x32_bf16 v[12:15], v[128:131], v[222:225], v[12:15]
	v_mfma_f32_16x16x32_bf16 v[4:7], v[136:139], v[222:225], v[4:7]
	v_mfma_f32_16x16x32_bf16 v[60:63], v[132:135], v[200:203], v[60:63]
	v_mfma_f32_16x16x32_bf16 v[52:55], v[168:171], v[200:203], v[52:55]
	v_mfma_f32_16x16x32_bf16 v[44:47], v[132:135], v[208:211], v[44:47]
	v_mfma_f32_16x16x32_bf16 v[36:39], v[168:171], v[208:211], v[36:39]
	v_mfma_f32_16x16x32_bf16 v[28:31], v[132:135], v[216:219], v[28:31]
	v_mfma_f32_16x16x32_bf16 v[20:23], v[168:171], v[216:219], v[20:23]
	v_mfma_f32_16x16x32_bf16 v[12:15], v[132:135], v[226:229], v[12:15]
	v_mfma_f32_16x16x32_bf16 v[4:7], v[168:171], v[226:229], v[4:7]
	s_setprio 0
	s_setprio 1
	v_mfma_f32_16x16x32_bf16 v[56:59], v[172:175], v[196:199], v[56:59]
	v_mfma_f32_16x16x32_bf16 v[48:51], v[188:191], v[196:199], v[48:51]
	v_mfma_f32_16x16x32_bf16 v[40:43], v[172:175], v[204:207], v[40:43]
	v_mfma_f32_16x16x32_bf16 v[32:35], v[188:191], v[204:207], v[32:35]
	v_mfma_f32_16x16x32_bf16 v[24:27], v[172:175], v[212:215], v[24:27]
	v_mfma_f32_16x16x32_bf16 v[16:19], v[188:191], v[212:215], v[16:19]
	v_mfma_f32_16x16x32_bf16 v[8:11], v[172:175], v[222:225], v[8:11]
	v_mfma_f32_16x16x32_bf16 v[0:3], v[188:191], v[222:225], v[0:3]
	v_mfma_f32_16x16x32_bf16 v[56:59], v[184:187], v[200:203], v[56:59]
	v_mfma_f32_16x16x32_bf16 v[48:51], v[192:195], v[200:203], v[48:51]
	v_mfma_f32_16x16x32_bf16 v[40:43], v[184:187], v[208:211], v[40:43]
	v_mfma_f32_16x16x32_bf16 v[32:35], v[192:195], v[208:211], v[32:35]
	v_mfma_f32_16x16x32_bf16 v[24:27], v[184:187], v[216:219], v[24:27]
	v_mfma_f32_16x16x32_bf16 v[16:19], v[192:195], v[216:219], v[16:19]
	v_mfma_f32_16x16x32_bf16 v[8:11], v[184:187], v[226:229], v[8:11]
	v_mfma_f32_16x16x32_bf16 v[0:3], v[192:195], v[226:229], v[0:3]
	s_setprio 0
	s_barrier
; #define PG8_STAGE(bufoff, gbase, voff) do { _Pragma("unroll") for (int _i = 0; _i < 2; ++_i) \
;         __builtin_amdgcn_global_load_lds((const unsigned*)((const char*)(gbase) + (voff)[_i]), (PG8_LAS unsigned*)(lds + (bufoff) + ldsw + _i * 8192), 16, 0, 0); } while (0)
; #define PG8_LDA(dst, b, h) do { _Pragma("unroll") for (int m = 0; m < 4; ++m) _Pragma("unroll") for (int k = 0; k < 2; ++k) dst[m][k] = *(const PG8_LAS bf16x8*)(lds + PG8_SA(b, h) + aoff + m * 2048 + k * 1024); } while (0)
; #define PG8_LDB(dst, b, h) do { _Pragma("unroll") for (int n = 0; n < 2; ++n) _Pragma("unroll") for (int k = 0; k < 2; ++k) dst[n][k] = *(const PG8_LAS bf16x8*)(lds + PG8_SB(b, h) + boff + n * 2048 + k * 1024); } while (0)
; #define PG8_MMA(ai, bj, At, Bt) do { __builtin_amdgcn_s_setprio(1); _Pragma("unroll") for (int m = 0; m < 4; ++m) _Pragma("unroll") for (int n = 0; n < 2; ++n) _Pragma("unroll") for (int k = 0; k < 2; ++k) \
;         acc[ai][bj][m][n] = __builtin_amdgcn_mfma_f32_16x16x32_bf16(Bt[n][k], At[m][k], acc[ai][bj][m][n], 0, 0, 0); __builtin_amdgcn_s_setprio(0); } while (0)
; #define PG8_WAIT_V(n) asm volatile("s_waitcnt vmcnt(" #n ")" ::: "memory")
; #define PG8_WAIT_L(n) asm volatile("s_waitcnt lgkmcnt(" #n ")" ::: "memory")
; #define PG8_BAR __builtin_amdgcn_s_barrier()
; #define PG8_SCHED __builtin_amdgcn_sched_barrier(0)
; template <class Epi, class Sched, bool ALIGN_EPI = false, bool SP2 = false, bool MIDHOOK = false>
; __device__ __forceinline__ void gemm_phase(PG8_LAS unsigned char* lds, const Gemm g, const Sched& S, const Epi& E) {
;     ...
;             PG8_LDB(B0, 1, 0); PG8_LDB(B1, 1, 1); PG8_SCHED; PG8_LDA(At, 1, 0); PG8_STAGE(PG8_SA(0, 1), a2 + hstep, voffA);
;             PG8_WAIT_V(8); PG8_WAIT_L(0); PG8_BAR; PG8_MMA(0, 0, At, B0); PG8_MMA(0, 1, At, B1); PG8_BAR; PG8_SCHED;
	s_add_i32 s66, 0, 0x18000
	v_add_u32_e32 v148, s66, v177
	s_add_i32 s67, 0, 0x1c000
	ds_read_b128 v[128:131], v148
	ds_read_b128 v[132:135], v148 offset:1024
	ds_read_b128 v[136:139], v148 offset:2048
	ds_read_b128 v[168:171], v148 offset:3072
	v_add_u32_e32 v148, s67, v177
	ds_read_b128 v[172:175], v148
	ds_read_b128 v[184:187], v148 offset:1024
	ds_read_b128 v[188:191], v148 offset:2048
	ds_read_b128 v[192:195], v148 offset:3072
	s_add_u32 s48, s48, 0x40000
	s_addc_u32 s49, s49, 0
	s_mov_b32 m0, s51
	v_lshl_add_u64 v[238:239], s[48:49], 0, v[140:141]
	ds_read_b128 v[196:199], v182 offset:32768
	ds_read_b128 v[200:203], v182 offset:33792
	ds_read_b128 v[204:207], v182 offset:34816
	ds_read_b128 v[208:211], v182 offset:35840
	ds_read_b128 v[212:215], v182 offset:36864
	ds_read_b128 v[216:219], v182 offset:37888
	ds_read_b128 v[222:225], v182 offset:38912
	ds_read_b128 v[226:229], v182 offset:39936
	global_load_lds_dwordx4 v[238:239], off
	v_lshl_add_u64 v[238:239], s[48:49], 0, v[144:145]
	s_mov_b32 m0, s52
	s_nop 0
	global_load_lds_dwordx4 v[238:239], off
	s_waitcnt vmcnt(8)
	s_waitcnt lgkmcnt(0)
	s_barrier
	s_setprio 1
	s_waitcnt lgkmcnt(0)
	v_mfma_f32_16x16x32_bf16 v[124:127], v[128:131], v[196:199], v[124:127]
	v_mfma_f32_16x16x32_bf16 v[116:119], v[136:139], v[196:199], v[116:119]
	v_mfma_f32_16x16x32_bf16 v[108:111], v[128:131], v[204:207], v[108:111]
	v_mfma_f32_16x16x32_bf16 v[100:103], v[136:139], v[204:207], v[100:103]
	v_mfma_f32_16x16x32_bf16 v[92:95], v[128:131], v[212:215], v[92:95]
	v_mfma_f32_16x16x32_bf16 v[84:87], v[136:139], v[212:215], v[84:87]
	v_mfma_f32_16x16x32_bf16 v[76:79], v[128:131], v[222:225], v[76:79]
	v_mfma_f32_16x16x32_bf16 v[68:71], v[136:139], v[222:225], v[68:71]
	v_mfma_f32_16x16x32_bf16 v[124:127], v[132:135], v[200:203], v[124:127]
	v_mfma_f32_16x16x32_bf16 v[116:119], v[168:171], v[200:203], v[116:119]
	v_mfma_f32_16x16x32_bf16 v[108:111], v[132:135], v[208:211], v[108:111]
	v_mfma_f32_16x16x32_bf16 v[100:103], v[168:171], v[208:211], v[100:103]
	v_mfma_f32_16x16x32_bf16 v[92:95], v[132:135], v[216:219], v[92:95]
	v_mfma_f32_16x16x32_bf16 v[84:87], v[168:171], v[216:219], v[84:87]
	v_mfma_f32_16x16x32_bf16 v[76:79], v[132:135], v[226:229], v[76:79]
	v_mfma_f32_16x16x32_bf16 v[68:71], v[168:171], v[226:229], v[68:71]
	s_setprio 0
	s_setprio 1
	v_mfma_f32_16x16x32_bf16 v[120:123], v[172:175], v[196:199], v[120:123]
	v_mfma_f32_16x16x32_bf16 v[112:115], v[188:191], v[196:199], v[112:115]
	v_mfma_f32_16x16x32_bf16 v[104:107], v[172:175], v[204:207], v[104:107]
	v_mfma_f32_16x16x32_bf16 v[96:99], v[188:191], v[204:207], v[96:99]
	v_mfma_f32_16x16x32_bf16 v[88:91], v[172:175], v[212:215], v[88:91]
	v_mfma_f32_16x16x32_bf16 v[80:83], v[188:191], v[212:215], v[80:83]
	v_mfma_f32_16x16x32_bf16 v[72:75], v[172:175], v[222:225], v[72:75]
	v_mfma_f32_16x16x32_bf16 v[64:67], v[188:191], v[222:225], v[64:67]
	v_mfma_f32_16x16x32_bf16 v[120:123], v[184:187], v[200:203], v[120:123]
	v_mfma_f32_16x16x32_bf16 v[112:115], v[192:195], v[200:203], v[112:115]
	v_mfma_f32_16x16x32_bf16 v[104:107], v[184:187], v[208:211], v[104:107]
	v_mfma_f32_16x16x32_bf16 v[96:99], v[192:195], v[208:211], v[96:99]
	v_mfma_f32_16x16x32_bf16 v[88:91], v[184:187], v[216:219], v[88:91]
	v_mfma_f32_16x16x32_bf16 v[80:83], v[192:195], v[216:219], v[80:83]
	v_mfma_f32_16x16x32_bf16 v[72:75], v[184:187], v[226:229], v[72:75]
	v_mfma_f32_16x16x32_bf16 v[64:67], v[192:195], v[226:229], v[64:67]
	s_setprio 0
	s_barrier
; #define PG8_STAGE(bufoff, gbase, voff) do { _Pragma("unroll") for (int _i = 0; _i < 2; ++_i) \
;         __builtin_amdgcn_global_load_lds((const unsigned*)((const char*)(gbase) + (voff)[_i]), (PG8_LAS unsigned*)(lds + (bufoff) + ldsw + _i * 8192), 16, 0, 0); } while (0)
; #define PG8_LDA(dst, b, h) do { _Pragma("unroll") for (int m = 0; m < 4; ++m) _Pragma("unroll") for (int k = 0; k < 2; ++k) dst[m][k] = *(const PG8_LAS bf16x8*)(lds + PG8_SA(b, h) + aoff + m * 2048 + k * 1024); } while (0)
; #define PG8_MMA(ai, bj, At, Bt) do { __builtin_amdgcn_s_setprio(1); _Pragma("unroll") for (int m = 0; m < 4; ++m) _Pragma("unroll") for (int n = 0; n < 2; ++n) _Pragma("unroll") for (int k = 0; k < 2; ++k) \
;         acc[ai][bj][m][n] = __builtin_amdgcn_mfma_f32_16x16x32_bf16(Bt[n][k], At[m][k], acc[ai][bj][m][n], 0, 0, 0); __builtin_amdgcn_s_setprio(0); } while (0)
; #define PG8_WAIT_V(n) asm volatile("s_waitcnt vmcnt(" #n ")" ::: "memory")
; #define PG8_WAIT_L(n) asm volatile("s_waitcnt lgkmcnt(" #n ")" ::: "memory")
; #define PG8_BAR __builtin_amdgcn_s_barrier()
; #define PG8_SCHED __builtin_amdgcn_sched_barrier(0)
; template <class Epi, class Sched, bool ALIGN_EPI = false, bool SP2 = false, bool MIDHOOK = false>
; __device__ __forceinline__ void gemm_phase(PG8_LAS unsigned char* lds, const Gemm g, const Sched& S, const Epi& E) {
;     ...
;             PG8_LDA(At, 1, 1); PG8_STAGE(PG8_SB(1, 0), b3, voffB); PG8_STAGE(PG8_SB(1, 1), b3 + hstep, voffB); PG8_STAGE(PG8_SA(1, 0), a3, voffA);
;             PG8_WAIT_V(8); PG8_WAIT_L(0); PG8_BAR; PG8_MMA(1, 0, At, B0); PG8_MMA(1, 1, At, B1); PG8_BAR; PG8_SCHED;
;     ...
;         if constexpr (ALIGN_EPI) { if (wr == 0) PG8_BAR; }
	s_add_i32 s48, s66, s3
	v_lshl_add_u64 v[230:231], v[230:231], 0, s[34:35]
	s_mov_b32 m0, s48
	ds_read_b128 v[196:199], v182 offset:49152
	ds_read_b128 v[200:203], v182 offset:50176
	ds_read_b128 v[204:207], v182 offset:51200
	ds_read_b128 v[208:211], v182 offset:52224
	ds_read_b128 v[212:215], v182 offset:53248
	ds_read_b128 v[216:219], v182 offset:54272
	ds_read_b128 v[222:225], v182 offset:55296
	ds_read_b128 v[226:229], v182 offset:56320
	global_load_lds_dwordx4 v[230:231], off
	s_add_i32 m0, s48, 0x2000
	s_add_u32 s8, s8, 0x40080
	v_lshl_add_u64 v[230:231], v[232:233], 0, s[34:35]
	s_addc_u32 s9, s9, 0
	s_add_i32 s48, s67, s3
	global_load_lds_dwordx4 v[230:231], off
	v_lshl_add_u64 v[230:231], s[8:9], 0, v[142:143]
	s_mov_b32 m0, s48
	s_nop 0
	global_load_lds_dwordx4 v[230:231], off
	v_lshl_add_u64 v[230:231], s[8:9], 0, v[146:147]
	s_add_i32 m0, s48, 0x2000
	s_nop 0
	global_load_lds_dwordx4 v[230:231], off
	v_lshl_add_u64 v[230:231], v[234:235], 0, s[34:35]
	s_mov_b32 m0, s54
	s_nop 0
	global_load_lds_dwordx4 v[230:231], off
	v_lshl_add_u64 v[230:231], v[236:237], 0, s[34:35]
	s_mov_b32 m0, s55
	s_nop 0
	global_load_lds_dwordx4 v[230:231], off
	s_waitcnt vmcnt(8)
	s_waitcnt lgkmcnt(0)
	s_barrier
	s_setprio 1
	s_waitcnt lgkmcnt(0)
	v_mfma_f32_16x16x32_bf16 v[60:63], v[128:131], v[196:199], v[60:63]
	v_mfma_f32_16x16x32_bf16 v[52:55], v[136:139], v[196:199], v[52:55]
	v_mfma_f32_16x16x32_bf16 v[44:47], v[128:131], v[204:207], v[44:47]
	v_mfma_f32_16x16x32_bf16 v[36:39], v[136:139], v[204:207], v[36:39]
	v_mfma_f32_16x16x32_bf16 v[28:31], v[128:131], v[212:215], v[28:31]
	v_mfma_f32_16x16x32_bf16 v[20:23], v[136:139], v[212:215], v[20:23]
	v_mfma_f32_16x16x32_bf16 v[12:15], v[128:131], v[222:225], v[12:15]
	v_mfma_f32_16x16x32_bf16 v[4:7], v[136:139], v[222:225], v[4:7]
	v_mfma_f32_16x16x32_bf16 v[60:63], v[132:135], v[200:203], v[60:63]
	v_mfma_f32_16x16x32_bf16 v[52:55], v[168:171], v[200:203], v[52:55]
	v_mfma_f32_16x16x32_bf16 v[44:47], v[132:135], v[208:211], v[44:47]
	v_mfma_f32_16x16x32_bf16 v[36:39], v[168:171], v[208:211], v[36:39]
	v_mfma_f32_16x16x32_bf16 v[28:31], v[132:135], v[216:219], v[28:31]
	v_mfma_f32_16x16x32_bf16 v[20:23], v[168:171], v[216:219], v[20:23]
	v_mfma_f32_16x16x32_bf16 v[12:15], v[132:135], v[226:229], v[12:15]
	v_mfma_f32_16x16x32_bf16 v[4:7], v[168:171], v[226:229], v[4:7]
	s_setprio 0
	s_setprio 1
	v_mfma_f32_16x16x32_bf16 v[56:59], v[172:175], v[196:199], v[56:59]
	v_mfma_f32_16x16x32_bf16 v[48:51], v[188:191], v[196:199], v[48:51]
	v_mfma_f32_16x16x32_bf16 v[40:43], v[172:175], v[204:207], v[40:43]
	v_mfma_f32_16x16x32_bf16 v[32:35], v[188:191], v[204:207], v[32:35]
	v_mfma_f32_16x16x32_bf16 v[24:27], v[172:175], v[212:215], v[24:27]
	v_mfma_f32_16x16x32_bf16 v[16:19], v[188:191], v[212:215], v[16:19]
	v_mfma_f32_16x16x32_bf16 v[8:11], v[172:175], v[222:225], v[8:11]
	v_mfma_f32_16x16x32_bf16 v[0:3], v[188:191], v[222:225], v[0:3]
	v_mfma_f32_16x16x32_bf16 v[56:59], v[184:187], v[200:203], v[56:59]
	v_mfma_f32_16x16x32_bf16 v[48:51], v[192:195], v[200:203], v[48:51]
	v_mfma_f32_16x16x32_bf16 v[40:43], v[184:187], v[208:211], v[40:43]
	v_mfma_f32_16x16x32_bf16 v[32:35], v[192:195], v[208:211], v[32:35]
	v_mfma_f32_16x16x32_bf16 v[24:27], v[184:187], v[216:219], v[24:27]
	v_mfma_f32_16x16x32_bf16 v[16:19], v[192:195], v[216:219], v[16:19]
	v_mfma_f32_16x16x32_bf16 v[8:11], v[184:187], v[226:229], v[8:11]
	v_mfma_f32_16x16x32_bf16 v[0:3], v[192:195], v[226:229], v[0:3]
	s_setprio 0
	s_barrier
	s_add_i32 s65, s65, 2
	s_add_u32 s6, s6, 0x100
	s_addc_u32 s7, s7, 0
	s_add_u32 s63, s63, 0x100
	s_addc_u32 s64, s64, 0
	s_cmp_gt_u32 s65, 13
	s_cbranch_scc0 .LBB0_191
	s_and_b64 vcc, exec, s[36:37]
	s_cbranch_vccz .LBB0_194
	s_barrier
